# P1 projection epilogue stores write-through (sc1): less dirty L2 for the leader's write-back at the following global barrier
# speedup vs baseline: 1.0066x; 1.0066x over previous
; __device__ __forceinline__ unsigned cvt_pk(float lo, float hi) { unsigned r; asm volatile("v_cvt_pk_bf16_f32 %0, %1, %2" : "=v"(r) : "v"(lo), "v"(hi)); return r; }
;     __device__ __forceinline__ void operator()(const pg8::f32x4 (&acc)[2][2][4][2], const pg8::Unit& u, int wr, int wc, int fr, int fq) const {
;         const int pn = u.pn; bf16* base; int ld, ct;
;         if (pn < 4) { base = Q; ld = DM; ct = pn; } else if (pn == 4) { base = K; ld = KVW; ct = 0; } else if (pn == 5) { base = V; ld = KVW; ct = 0; } else { base = U; ld = DM; ct = pn - 6; }
;         const int row0 = u.pm * 256 + wr * 64 + fr, col0 = ct * 256 + wc * 32 + 8 * fq;
;         float rsv[8];
; #pragma unroll
;         for (int q = 0; q < 8; ++q) rsv[q] = rstd[row0 + (q >> 2) * 128 + (q & 3) * 16];
;         asm volatile("" : "+v"(rsv[0]), "+v"(rsv[1]), "+v"(rsv[2]), "+v"(rsv[3]), "+v"(rsv[4]), "+v"(rsv[5]), "+v"(rsv[6]), "+v"(rsv[7]));
; #pragma unroll
;         for (int ai = 0; ai < 2; ++ai)
; #pragma unroll
;             for (int m = 0; m < 4; ++m) { const int row = row0 + ai * 128 + m * 16; const float rs = rsv[ai * 4 + m]; bf16* rowp = base + (size_t)row * ld + col0;
; #pragma unroll
;                 for (int bj = 0; bj < 2; ++bj) { pg8::f32x4 v0 = acc[ai][bj][m][0] * rs, v1 = acc[ai][bj][m][1] * rs;
;                     u32x4 w; w.x = cvt_pk(v0[0], v0[1]); w.y = cvt_pk(v0[2], v0[3]); w.z = cvt_pk(v1[0], v1[1]); w.w = cvt_pk(v1[2], v1[3]);
;                     *(u32x4*)(rowp + bj * 128) = w; } }
;     }
.LBB0_189:
	v_lshl_add_u32 v142, s22, 8, v145
	v_ashrrev_i32_e32 v143, 31, v142
	v_lshl_add_u64 v[150:151], v[142:143], 2, s[58:59]
	global_load_dword v140, v[150:151], off offset:704
	global_load_dword v144, v[150:151], off offset:640
	global_load_dword v146, v[150:151], off offset:576
	global_load_dword v148, v[150:151], off offset:512
	global_load_dword v152, v[150:151], off offset:192
	global_load_dword v156, v[150:151], off offset:128
	global_load_dword v158, v[150:151], off offset:64
	global_load_dword v170, v[150:151], off
	v_lshl_or_b32 v150, s63, 8, v149
	v_ashrrev_i32_e32 v151, 31, v150
	v_mad_i64_i32 v[172:173], s[28:29], s24, v142, 0
	v_or_b32_e32 v157, 16, v142
	v_or_b32_e32 v159, 32, v142
	v_lshl_add_u64 v[150:151], v[150:151], 1, s[26:27]
	v_mad_i64_i32 v[174:175], s[26:27], s24, v157, 0
	v_mad_i64_i32 v[176:177], s[26:27], s24, v159, 0
	v_lshl_add_u64 v[172:173], v[172:173], 1, v[150:151]
	v_lshl_add_u64 v[174:175], v[174:175], 1, v[150:151]
	v_or_b32_e32 v161, 48, v142
	v_lshl_add_u64 v[176:177], v[176:177], 1, v[150:151]
	v_mad_i64_i32 v[178:179], s[26:27], s24, v161, 0
	v_lshl_add_u64 v[178:179], v[178:179], 1, v[150:151]
	v_add_u32_e32 v143, 0x80, v142
	s_andn2_b64 vcc, exec, s[0:1]
	s_mov_b64 s[0:1], -1
	s_waitcnt vmcnt(0)
	s_nop 0
	v_pk_mul_f32 v[126:127], v[126:127], v[170:171] op_sel_hi:[1,0]
	v_pk_mul_f32 v[124:125], v[124:125], v[170:171] op_sel_hi:[1,0]
	v_pk_mul_f32 v[118:119], v[118:119], v[158:159] op_sel_hi:[1,0]
	v_pk_mul_f32 v[116:117], v[116:117], v[158:159] op_sel_hi:[1,0]
	v_pk_mul_f32 v[114:115], v[114:115], v[158:159] op_sel_hi:[1,0]
	v_pk_mul_f32 v[112:113], v[112:113], v[158:159] op_sel_hi:[1,0]
	v_pk_mul_f32 v[90:91], v[90:91], v[158:159] op_sel_hi:[1,0]
	v_pk_mul_f32 v[88:89], v[88:89], v[158:159] op_sel_hi:[1,0]
	v_pk_mul_f32 v[86:87], v[86:87], v[158:159] op_sel_hi:[1,0]
	v_pk_mul_f32 v[84:85], v[84:85], v[158:159] op_sel_hi:[1,0]
	v_pk_mul_f32 v[110:111], v[110:111], v[156:157] op_sel_hi:[1,0]
	v_pk_mul_f32 v[108:109], v[108:109], v[156:157] op_sel_hi:[1,0]
	v_pk_mul_f32 v[102:103], v[102:103], v[156:157] op_sel_hi:[1,0]
	v_pk_mul_f32 v[100:101], v[100:101], v[156:157] op_sel_hi:[1,0]
	v_pk_mul_f32 v[78:79], v[78:79], v[156:157] op_sel_hi:[1,0]
	v_pk_mul_f32 v[76:77], v[76:77], v[156:157] op_sel_hi:[1,0]
	v_pk_mul_f32 v[158:159], v[74:75], v[156:157] op_sel_hi:[1,0]
	v_pk_mul_f32 v[156:157], v[72:73], v[156:157] op_sel_hi:[1,0]
	v_cvt_pk_bf16_f32 v72, v124, v125
	v_cvt_pk_bf16_f32 v73, v126, v127
	v_pk_mul_f32 v[122:123], v[122:123], v[170:171] op_sel_hi:[1,0]
	v_pk_mul_f32 v[120:121], v[120:121], v[170:171] op_sel_hi:[1,0]
	v_pk_mul_f32 v[106:107], v[106:107], v[170:171] op_sel_hi:[1,0]
	v_pk_mul_f32 v[104:105], v[104:105], v[170:171] op_sel_hi:[1,0]
	v_cvt_pk_bf16_f32 v74, v120, v121
	v_cvt_pk_bf16_f32 v75, v122, v123
	global_store_dwordx4 v[172:173], v[72:75], off sc1
	v_pk_mul_f32 v[98:99], v[98:99], v[170:171] op_sel_hi:[1,0]
	v_pk_mul_f32 v[96:97], v[96:97], v[170:171] op_sel_hi:[1,0]
	v_cvt_pk_bf16_f32 v72, v104, v105
	v_cvt_pk_bf16_f32 v73, v106, v107
	v_pk_mul_f32 v[94:95], v[94:95], v[152:153] op_sel_hi:[1,0]
	v_cvt_pk_bf16_f32 v74, v96, v97
	v_cvt_pk_bf16_f32 v75, v98, v99
	global_store_dwordx4 v[172:173], v[72:75], off offset:256 sc1
	v_pk_mul_f32 v[92:93], v[92:93], v[152:153] op_sel_hi:[1,0]
	v_pk_mul_f32 v[82:83], v[82:83], v[152:153] op_sel_hi:[1,0]
	v_cvt_pk_bf16_f32 v72, v116, v117
	v_cvt_pk_bf16_f32 v73, v118, v119
	v_cvt_pk_bf16_f32 v74, v112, v113
	v_cvt_pk_bf16_f32 v75, v114, v115
	global_store_dwordx4 v[174:175], v[72:75], off sc1
	v_pk_mul_f32 v[80:81], v[80:81], v[152:153] op_sel_hi:[1,0]
	v_pk_mul_f32 v[70:71], v[70:71], v[152:153] op_sel_hi:[1,0]
	v_cvt_pk_bf16_f32 v72, v88, v89
	v_cvt_pk_bf16_f32 v73, v90, v91
	v_cvt_pk_bf16_f32 v74, v84, v85
	v_cvt_pk_bf16_f32 v75, v86, v87
	global_store_dwordx4 v[174:175], v[72:75], off offset:256 sc1
	v_pk_mul_f32 v[68:69], v[68:69], v[152:153] op_sel_hi:[1,0]
	v_pk_mul_f32 v[62:63], v[62:63], v[148:149] op_sel_hi:[1,0]
	v_cvt_pk_bf16_f32 v72, v108, v109
	v_cvt_pk_bf16_f32 v73, v110, v111
	v_cvt_pk_bf16_f32 v74, v100, v101
	v_cvt_pk_bf16_f32 v75, v102, v103
	global_store_dwordx4 v[176:177], v[72:75], off sc1
	v_pk_mul_f32 v[60:61], v[60:61], v[148:149] op_sel_hi:[1,0]
	v_pk_mul_f32 v[52:53], v[52:53], v[148:149] op_sel_hi:[1,0]
	v_cvt_pk_bf16_f32 v72, v76, v77
	v_cvt_pk_bf16_f32 v73, v78, v79
	v_cvt_pk_bf16_f32 v74, v156, v157
	v_cvt_pk_bf16_f32 v75, v158, v159
; __device__ __forceinline__ unsigned cvt_pk(float lo, float hi) { unsigned r; asm volatile("v_cvt_pk_bf16_f32 %0, %1, %2" : "=v"(r) : "v"(lo), "v"(hi)); return r; }
;     __device__ __forceinline__ void operator()(const pg8::f32x4 (&acc)[2][2][4][2], const pg8::Unit& u, int wr, int wc, int fr, int fq) const {
;     ...
;             for (int m = 0; m < 4; ++m) { const int row = row0 + ai * 128 + m * 16; const float rs = rsv[ai * 4 + m]; bf16* rowp = base + (size_t)row * ld + col0;
; #pragma unroll
;                 for (int bj = 0; bj < 2; ++bj) { pg8::f32x4 v0 = acc[ai][bj][m][0] * rs, v1 = acc[ai][bj][m][1] * rs;
;                     u32x4 w; w.x = cvt_pk(v0[0], v0[1]); w.y = cvt_pk(v0[2], v0[3]); w.z = cvt_pk(v1[0], v1[1]); w.w = cvt_pk(v1[2], v1[3]);
;                     *(u32x4*)(rowp + bj * 128) = w; } }
	global_store_dwordx4 v[176:177], v[72:75], off offset:256 sc1
	v_pk_mul_f32 v[54:55], v[54:55], v[148:149] op_sel_hi:[1,0]
	v_pk_mul_f32 v[48:49], v[48:49], v[146:147] op_sel_hi:[1,0]
	v_cvt_pk_bf16_f32 v72, v92, v93
	v_cvt_pk_bf16_f32 v73, v94, v95
	v_cvt_pk_bf16_f32 v74, v80, v81
	v_cvt_pk_bf16_f32 v75, v82, v83
	global_store_dwordx4 v[178:179], v[72:75], off sc1
	v_pk_mul_f32 v[36:37], v[36:37], v[146:147] op_sel_hi:[1,0]
	v_pk_mul_f32 v[38:39], v[38:39], v[146:147] op_sel_hi:[1,0]
	v_pk_mul_f32 v[72:73], v[66:67], v[152:153] op_sel_hi:[1,0]
	v_pk_mul_f32 v[66:67], v[64:65], v[152:153] op_sel_hi:[1,0]
	v_cvt_pk_bf16_f32 v64, v68, v69
	v_cvt_pk_bf16_f32 v65, v70, v71
	v_pk_mul_f32 v[32:33], v[32:33], v[144:145] op_sel_hi:[1,0]
	v_cvt_pk_bf16_f32 v66, v66, v67
	v_cvt_pk_bf16_f32 v67, v72, v73
	global_store_dwordx4 v[178:179], v[64:67], off offset:256 sc1
	v_pk_mul_f32 v[20:21], v[20:21], v[144:145] op_sel_hi:[1,0]
	v_pk_mul_f32 v[22:23], v[22:23], v[144:145] op_sel_hi:[1,0]
	v_mad_i64_i32 v[64:65], s[26:27], s24, v143, 0
	v_lshl_add_u64 v[64:65], v[64:65], 1, v[150:151]
	v_pk_mul_f32 v[66:67], v[58:59], v[148:149] op_sel_hi:[1,0]
	v_pk_mul_f32 v[58:59], v[56:57], v[148:149] op_sel_hi:[1,0]
	v_cvt_pk_bf16_f32 v56, v60, v61
	v_cvt_pk_bf16_f32 v57, v62, v63
	v_pk_mul_f32 v[16:17], v[16:17], v[140:141] op_sel_hi:[1,0]
	v_cvt_pk_bf16_f32 v58, v58, v59
	v_cvt_pk_bf16_f32 v59, v66, v67
	global_store_dwordx4 v[64:65], v[56:59], off sc1
	v_pk_mul_f32 v[6:7], v[6:7], v[140:141] op_sel_hi:[1,0]
	v_pk_mul_f32 v[4:5], v[4:5], v[140:141] op_sel_hi:[1,0]
	v_pk_mul_f32 v[56:57], v[46:47], v[148:149] op_sel_hi:[1,0]
	v_pk_mul_f32 v[46:47], v[44:45], v[148:149] op_sel_hi:[1,0]
	v_cvt_pk_bf16_f32 v44, v52, v53
	v_cvt_pk_bf16_f32 v45, v54, v55
	s_nop 0
	v_cvt_pk_bf16_f32 v46, v46, v47
	v_cvt_pk_bf16_f32 v47, v56, v57
	global_store_dwordx4 v[64:65], v[44:47], off offset:256 sc1
	s_nop 1
	v_add_u32_e32 v44, 0x90, v142
	v_mad_i64_i32 v[44:45], s[26:27], s24, v44, 0
	v_lshl_add_u64 v[44:45], v[44:45], 1, v[150:151]
	v_pk_mul_f32 v[46:47], v[50:51], v[146:147] op_sel_hi:[1,0]
	v_pk_mul_f32 v[50:51], v[42:43], v[146:147] op_sel_hi:[1,0]
	v_pk_mul_f32 v[42:43], v[40:41], v[146:147] op_sel_hi:[1,0]
	v_cvt_pk_bf16_f32 v40, v48, v49
	v_cvt_pk_bf16_f32 v41, v46, v47
	s_nop 0
	v_cvt_pk_bf16_f32 v42, v42, v43
	v_cvt_pk_bf16_f32 v43, v50, v51
	global_store_dwordx4 v[44:45], v[40:43], off sc1
	s_nop 1
	v_pk_mul_f32 v[40:41], v[30:31], v[146:147] op_sel_hi:[1,0]
	v_pk_mul_f32 v[30:31], v[28:29], v[146:147] op_sel_hi:[1,0]
	v_cvt_pk_bf16_f32 v28, v36, v37
	v_cvt_pk_bf16_f32 v29, v38, v39
	s_nop 0
	v_cvt_pk_bf16_f32 v30, v30, v31
	v_cvt_pk_bf16_f32 v31, v40, v41
	global_store_dwordx4 v[44:45], v[28:31], off offset:256 sc1
	s_nop 1
	v_add_u32_e32 v28, 0xa0, v142
	v_mad_i64_i32 v[28:29], s[26:27], s24, v28, 0
	v_lshl_add_u64 v[28:29], v[28:29], 1, v[150:151]
	v_pk_mul_f32 v[30:31], v[34:35], v[144:145] op_sel_hi:[1,0]
	v_pk_mul_f32 v[34:35], v[26:27], v[144:145] op_sel_hi:[1,0]
	v_pk_mul_f32 v[26:27], v[24:25], v[144:145] op_sel_hi:[1,0]
	v_cvt_pk_bf16_f32 v24, v32, v33
	v_cvt_pk_bf16_f32 v25, v30, v31
	s_nop 0
	v_cvt_pk_bf16_f32 v26, v26, v27
	v_cvt_pk_bf16_f32 v27, v34, v35
	global_store_dwordx4 v[28:29], v[24:27], off sc1
	s_nop 1
	v_pk_mul_f32 v[24:25], v[14:15], v[144:145] op_sel_hi:[1,0]
	v_pk_mul_f32 v[14:15], v[12:13], v[144:145] op_sel_hi:[1,0]
	v_cvt_pk_bf16_f32 v12, v20, v21
	v_cvt_pk_bf16_f32 v13, v22, v23
	s_nop 0
	v_cvt_pk_bf16_f32 v14, v14, v15
	v_cvt_pk_bf16_f32 v15, v24, v25
	global_store_dwordx4 v[28:29], v[12:15], off offset:256 sc1
	s_nop 1
	v_add_u32_e32 v12, 0xb0, v142
	v_mad_i64_i32 v[12:13], s[24:25], s24, v12, 0
	v_lshl_add_u64 v[12:13], v[12:13], 1, v[150:151]
	v_pk_mul_f32 v[14:15], v[18:19], v[140:141] op_sel_hi:[1,0]
	v_pk_mul_f32 v[18:19], v[10:11], v[140:141] op_sel_hi:[1,0]
	v_pk_mul_f32 v[10:11], v[8:9], v[140:141] op_sel_hi:[1,0]
	v_cvt_pk_bf16_f32 v8, v16, v17
	v_cvt_pk_bf16_f32 v9, v14, v15
	s_nop 0
	v_cvt_pk_bf16_f32 v10, v10, v11
	v_cvt_pk_bf16_f32 v11, v18, v19
	global_store_dwordx4 v[12:13], v[8:11], off sc1
	s_nop 1
	v_pk_mul_f32 v[8:9], v[2:3], v[140:141] op_sel_hi:[1,0]
	v_pk_mul_f32 v[2:3], v[0:1], v[140:141] op_sel_hi:[1,0]
	v_cvt_pk_bf16_f32 v0, v4, v5
	v_cvt_pk_bf16_f32 v1, v6, v7
	s_nop 0
	v_cvt_pk_bf16_f32 v2, v2, v3
	v_cvt_pk_bf16_f32 v3, v8, v9
	global_store_dwordx4 v[12:13], v[0:3], off offset:256 sc1
	s_cbranch_vccnz .LBB0_174
	s_andn2_b64 vcc, exec, s[8:9]
	s_cbranch_vccnz .LBB0_173
	s_barrier
	s_branch .LBB0_173
